# v30 plus M1 column-sum tile swizzle, batched weight-item tail reads, M3 denominator-row prefetch (each neutral alone)
# speedup vs baseline: 1.0019x; 1.0019x over previous
.LBB0_733:
	s_or_b64 exec, exec, s[2:3]
	s_waitcnt lgkmcnt(0)
	v_mul_u32_u24_e32 v3, 0x90, v156
	v_lshrrev_b32_e32 v69, 3, v159
	v_bfe_u32 v199, v156, 3, 3
	v_xor_b32_e32 v69, v69, v199
	v_lshlrev_b32_e32 v199, 1, v159
	v_and_b32_e32 v199, 15, v199
	v_lshl_or_b32 v69, v69, 4, v199
	s_waitcnt vmcnt(5)
	v_and_b32_e32 v2, 0xffff, v60
	v_add3_u32 v3, 0, v3, v69
	v_lshrrev_b32_e32 v60, 16, v60
	s_waitcnt vmcnt(4)
	v_lshl_or_b32 v2, v64, 16, v2
	v_and_or_b32 v60, v64, s47, v60
	v_add_u32_e32 v3, 0x8800, v3
	ds_write2_b32 v3, v2, v60 offset1:36
	v_and_b32_e32 v2, 0xffff, v61
	v_lshrrev_b32_e32 v60, 16, v61
	v_lshl_or_b32 v2, v65, 16, v2
	v_and_or_b32 v60, v65, s47, v60
	ds_write2_b32 v3, v2, v60 offset0:72 offset1:108
	v_and_b32_e32 v2, 0xffff, v62
	v_lshrrev_b32_e32 v60, 16, v62
	v_lshl_or_b32 v2, v66, 16, v2
	v_and_or_b32 v60, v66, s47, v60
	ds_write2_b32 v3, v2, v60 offset0:144 offset1:180
	v_and_b32_e32 v2, 0xffff, v63
	v_lshrrev_b32_e32 v60, 16, v63
	s_add_u32 s0, s34, s58
	v_ashrrev_i32_e32 v86, 4, v157
	v_lshl_or_b32 v2, v67, 16, v2
	v_and_or_b32 v60, v67, s47, v60
	s_addc_u32 s1, s35, 0
	v_lshlrev_b32_e32 v82, 1, v156
	v_mov_b32_e32 v83, v0
	v_ashrrev_i32_e32 v87, 31, v86
	ds_write2_b32 v3, v2, v60 offset0:216 offset1:252
	v_lshl_add_u64 v[60:61], s[0:1], 0, v[82:83]
	v_lshl_add_u64 v[84:85], s[26:27], 0, v[86:87]
	v_mad_u64_u32 v[62:63], s[0:1], v84, s33, v[60:61]
	v_mov_b32_e32 v2, v63
	v_mad_u64_u32 v[2:3], s[0:1], v85, s33, v[2:3]
	v_mov_b32_e32 v63, v2
	v_add_u32_e32 v2, 0x200, v157
	v_ashrrev_i32_e32 v2, 4, v2
	v_ashrrev_i32_e32 v3, 31, v2
	v_lshl_add_u64 v[80:81], s[26:27], 0, v[2:3]
	v_mad_u64_u32 v[60:61], s[0:1], v80, s33, v[60:61]
	v_lshlrev_b32_e32 v68, 3, v89
	v_mov_b32_e32 v64, v61
	v_mad_u64_u32 v[64:65], s[0:1], v81, s33, v[64:65]
	v_lshlrev_b32_e32 v3, 1, v68
	v_mul_u32_u24_e32 v68, 0x90, v88
	v_mov_b32_e32 v61, v64
	v_add3_u32 v83, s50, v3, v68
	global_load_dwordx4 v[64:67], v[62:63], off
	s_nop 0
	global_load_dwordx4 v[60:63], v[60:61], off
	s_waitcnt lgkmcnt(0)
	s_barrier
	ds_read_b128 v[68:71], v83
	v_lshl_or_b32 v72, v91, 4, v88
	v_mul_lo_u32 v72, v72, s52
	v_lshrrev_b32_e32 v199, 3, v88
	v_lshl_or_b32 v199, v91, 1, v199
	v_and_b32_e32 v199, 7, v199
	v_lshrrev_b32_e32 v3, 4, v3
	v_xor_b32_e32 v199, v3, v199
	v_lshl_add_u32 v3, v199, 4, v72
	v_xor_b32_e32 v199, 4, v199
	v_lshl_add_u32 v199, v199, 4, v72
	ds_read_b128 v[72:75], v3 offset:34816
	ds_read_b128 v[92:95], v199 offset:34816
	ds_read_b128 v[76:79], v83 offset:64
	ds_read_b128 v[96:99], v83 offset:2304
	ds_read_b128 v[100:103], v83 offset:2368
	ds_read_b128 v[104:107], v83 offset:4608
	ds_read_b128 v[108:111], v83 offset:4672
	ds_read_b128 v[112:115], v83 offset:6912
	ds_read_b128 v[116:119], v83 offset:6976
	s_waitcnt lgkmcnt(8)
	v_mfma_f32_16x16x32_bf16 v[68:71], v[68:71], v[72:75], 0
	v_and_b32_e32 v3, 48, v157
	v_mul_u32_u24_e32 v83, 0x110, v88
	v_add3_u32 v3, 0, v3, v83
	s_waitcnt lgkmcnt(5)
	v_mfma_f32_16x16x32_bf16 v[96:99], v[96:99], v[72:75], 0
	v_lshl_add_u32 v91, v91, 2, s54
	s_waitcnt lgkmcnt(3)
	v_mfma_f32_16x16x32_bf16 v[104:107], v[104:107], v[72:75], 0
	s_waitcnt lgkmcnt(1)
	v_mfma_f32_16x16x32_bf16 v[112:115], v[112:115], v[72:75], 0
	v_mfma_f32_16x16x32_bf16 v[120:123], v[76:79], v[92:95], v[68:71]
	v_mfma_f32_16x16x32_bf16 v[76:79], v[100:103], v[92:95], v[96:99]
	v_mfma_f32_16x16x32_bf16 v[72:75], v[108:111], v[92:95], v[104:107]
	s_waitcnt lgkmcnt(0)
	v_mfma_f32_16x16x32_bf16 v[68:71], v[116:119], v[92:95], v[112:115]
	ds_read_b128 v[92:95], v3
	ds_read_b128 v[96:99], v3 offset:64
	ds_read_b128 v[100:103], v3 offset:4352
	ds_read_b128 v[104:107], v3 offset:4416
	ds_read_b128 v[108:111], v3 offset:8704
	ds_read_b128 v[112:115], v3 offset:8768
	ds_read_b128 v[116:119], v3 offset:13056
	ds_read_b128 v[124:127], v3 offset:13120
	s_waitcnt vmcnt(5) lgkmcnt(7)
	v_mfma_f32_16x16x32_bf16 v[92:95], v[92:95], v[56:59], 0
	s_waitcnt lgkmcnt(5)
	v_mfma_f32_16x16x32_bf16 v[100:103], v[100:103], v[56:59], 0
	s_waitcnt lgkmcnt(3)
	v_mfma_f32_16x16x32_bf16 v[108:111], v[108:111], v[56:59], 0
	s_waitcnt lgkmcnt(1)
	v_mfma_f32_16x16x32_bf16 v[56:59], v[116:119], v[56:59], 0
	s_waitcnt vmcnt(4)
	v_mfma_f32_16x16x32_bf16 v[92:95], v[96:99], v[52:55], v[92:95]
	v_mfma_f32_16x16x32_bf16 v[96:99], v[104:107], v[52:55], v[100:103]
	v_mfma_f32_16x16x32_bf16 v[100:103], v[112:115], v[52:55], v[108:111]
	s_waitcnt lgkmcnt(0)
	v_mfma_f32_16x16x32_bf16 v[52:55], v[124:127], v[52:55], v[56:59]
	s_nop 2
	ds_read_b128 v[56:59], v3 offset:128
	ds_read_b128 v[104:107], v3 offset:192
	s_waitcnt vmcnt(3) lgkmcnt(1)
	v_mfma_f32_16x16x32_bf16 v[56:59], v[56:59], v[48:51], v[92:95]
	s_nop 2
	ds_read_b128 v[92:95], v3 offset:4480
	ds_read_b128 v[108:111], v3 offset:4544
	s_waitcnt lgkmcnt(1)
	v_mfma_f32_16x16x32_bf16 v[92:95], v[92:95], v[48:51], v[96:99]
	s_nop 2
	ds_read_b128 v[96:99], v3 offset:8832
	ds_read_b128 v[112:115], v3 offset:8896
	s_waitcnt lgkmcnt(1)
	v_mfma_f32_16x16x32_bf16 v[96:99], v[96:99], v[48:51], v[100:103]
	s_nop 2
	ds_read_b128 v[100:103], v3 offset:13184
	ds_read_b128 v[116:119], v3 offset:13248
	v_lshl_add_u32 v3, v90, 2, 0
	v_add_u32_e32 v83, 0x17f00, v3
	s_waitcnt vmcnt(2)
	v_mfma_f32_16x16x32_bf16 v[104:107], v[104:107], v[44:47], v[56:59]
	s_nop 2
	v_add_u32_e32 v56, 0x17e00, v3
	v_lshl_add_u32 v57, v89, 6, s53
	s_waitcnt lgkmcnt(1)
	v_mfma_f32_16x16x32_bf16 v[100:103], v[100:103], v[48:51], v[52:55]
	v_add_u32_e32 v3, 0x18000, v3
	v_mfma_f32_16x16x32_bf16 v[52:55], v[108:111], v[44:47], v[92:95]
	v_mfma_f32_16x16x32_bf16 v[48:51], v[112:115], v[44:47], v[96:99]
	s_nop 2
	ds_read_b128 v[162:165], v57 offset:16
	ds_read_b128 v[166:169], v57 offset:32
	ds_read_b128 v[170:173], v57 offset:48
	ds_read_b128 v[174:177], v57 offset:272
	ds_read_b128 v[178:181], v57 offset:288
	ds_read_b128 v[182:185], v57 offset:304
	ds_read_b128 v[186:189], v57 offset:528
	ds_read_b128 v[190:193], v57 offset:544
	ds_read_b128 v[194:197], v57 offset:560
	ds_read_b128 v[198:201], v57 offset:784
	ds_read_b128 v[202:205], v57 offset:800
	ds_read_b128 v[206:209], v57 offset:816
	ds_read_b128 v[94:97], v56
	ds_read_b128 v[56:59], v57
	ds_read_b128 v[108:111], v83
	ds_read_b128 v[112:115], v3
	v_mov_b32_e32 v93, v0
	s_waitcnt lgkmcnt(4)
	v_mfma_f32_16x16x32_bf16 v[44:47], v[116:119], v[44:47], v[100:103]
	s_waitcnt lgkmcnt(3)
	v_mul_f32_e32 v97, 0xbfb8aa3b, v97
	s_waitcnt lgkmcnt(2)
	v_add_f32_e32 v3, v56, v57
	v_mul_f32_e32 v56, 0xbfb8aa3b, v94
	v_exp_f32_e32 v56, v56
	v_add_f32_e32 v57, v58, v59
	v_add_f32_e32 v3, v3, v57
	s_waitcnt lgkmcnt(0)
	v_fmac_f32_e32 v3, v108, v112
	v_max_f32_e64 v3, |v3|, v56
	v_rcp_f32_e32 v3, v3
	v_fma_f32 v56, v104, v108, v120
	v_mov_b32_e32 v57, v0
	v_mul_f32_e32 v59, 0xbfb8aa3b, v95
	v_mul_f32_e32 v56, v56, v3
	v_mul_f32_e32 v3, v56, v56
	v_exp_f32_e32 v59, v59
	v_exp_f32_e32 v97, v97
	v_mov_b32_dpp v57, v3 row_ror:8 row_mask:0xf bank_mask:0xf
	v_or_b32_e32 v3, 1, v90
	v_lshl_add_u32 v58, v3, 4, s53
	v_fmac_f32_e32 v57, v56, v56
	v_fmac_f32_e32 v123, v107, v111
	v_mov_b32_e32 v95, v0
	v_add_f32_dpp v57, v57, v57 row_ror:4 row_mask:0xf bank_mask:0xf bound_ctrl:1
	s_waitcnt lgkmcnt(0)
	v_add_f32_e32 v83, v164, v165
	v_add_f32_dpp v92, v57, v57 row_ror:2 row_mask:0xf bank_mask:0xf bound_ctrl:1
	v_or_b32_e32 v57, 2, v90
	v_lshl_add_u32 v58, v57, 4, s53
	v_add_f32_e32 v58, v162, v163
	v_add_f32_e32 v58, v58, v83
	v_fmac_f32_e32 v58, v109, v113
	v_max_f32_e64 v58, |v58|, v59
	v_rcp_f32_e32 v58, v58
	v_fma_f32 v59, v105, v109, v121
	v_mov_b32_e32 v83, v0
	s_waitcnt lgkmcnt(0)
	v_add_f32_e32 v87, v168, v169
	v_mul_f32_e32 v59, v59, v58
	v_mul_f32_e32 v58, v59, v59
	v_mov_b32_dpp v93, v92 row_ror:1 row_mask:0xf bank_mask:0xf
	s_nop 0
	v_mov_b32_dpp v83, v58 row_ror:8 row_mask:0xf bank_mask:0xf
	v_fmac_f32_e32 v83, v59, v59
	s_nop 1
	v_add_f32_dpp v58, v83, v83 row_ror:4 row_mask:0xf bank_mask:0xf bound_ctrl:1
	v_mul_f32_e32 v83, 0xbfb8aa3b, v96
	v_exp_f32_e32 v83, v83
	v_add_f32_dpp v94, v58, v58 row_ror:2 row_mask:0xf bank_mask:0xf bound_ctrl:1
	v_add_f32_e32 v58, v166, v167
	v_add_f32_e32 v58, v58, v87
	v_fmac_f32_e32 v58, v110, v114
	v_max_f32_e64 v58, |v58|, v83
	v_rcp_f32_e32 v58, v58
	v_or_b32_e32 v87, 3, v90
	v_fma_f32 v83, v106, v110, v122
	v_lshl_add_u32 v98, v87, 4, s53
	v_mul_f32_e32 v58, v83, v58
	v_mul_f32_e32 v83, v58, v58
	v_mov_b32_e32 v96, v0
	v_mov_b32_dpp v95, v94 row_ror:1 row_mask:0xf bank_mask:0xf
	s_nop 0
	v_mov_b32_dpp v96, v83 row_ror:8 row_mask:0xf bank_mask:0xf
	v_fmac_f32_e32 v96, v58, v58
	s_nop 1
	v_add_f32_dpp v83, v96, v96 row_ror:4 row_mask:0xf bank_mask:0xf bound_ctrl:1
	s_nop 1
	v_add_f32_dpp v96, v83, v83 row_ror:2 row_mask:0xf bank_mask:0xf bound_ctrl:1
	s_waitcnt lgkmcnt(0)
	v_add_f32_e32 v83, v170, v171
	v_add_f32_e32 v98, v172, v173
	v_add_f32_e32 v83, v83, v98
	v_fmac_f32_e32 v83, v111, v115
	v_max_f32_e64 v83, |v83|, v97
	v_rcp_f32_e32 v83, v83
	v_mov_b32_e32 v99, v0
	v_mov_b32_e32 v97, v0
	v_mul_f32_e32 v83, v123, v83
	v_mul_f32_e32 v98, v83, v83
	v_mov_b32_dpp v97, v96 row_ror:1 row_mask:0xf bank_mask:0xf
	s_nop 0
	v_mov_b32_dpp v99, v98 row_ror:8 row_mask:0xf bank_mask:0xf
	v_fmac_f32_e32 v99, v83, v83
	s_nop 1
	v_add_f32_dpp v98, v99, v99 row_ror:4 row_mask:0xf bank_mask:0xf bound_ctrl:1
	v_mov_b32_e32 v99, v0
	s_nop 0
	v_add_f32_dpp v98, v98, v98 row_ror:2 row_mask:0xf bank_mask:0xf bound_ctrl:1
	s_nop 1
	v_mov_b32_dpp v99, v98 row_ror:1 row_mask:0xf bank_mask:0xf
	s_and_saveexec_b64 s[0:1], s[12:13]
	s_cbranch_execz .LBB0_735
	v_add_f32_e32 v92, v92, v93
	v_lshl_add_u32 v93, v89, 7, v91
	v_add_f32_e32 v94, v94, v95
	ds_write_b32 v93, v92
	v_lshl_add_u32 v92, v3, 5, v91
	v_add_f32_e32 v96, v96, v97
	ds_write_b32 v92, v94
	v_lshl_add_u32 v92, v57, 5, v91
	v_add_f32_e32 v98, v98, v99
	ds_write_b32 v92, v96
	v_lshl_add_u32 v92, v87, 5, v91
	ds_write_b32 v92, v98
